# v6a: + attention output (OB) stores write-through (sc1)
# speedup vs baseline: 1.0383x; 1.0079x over previous
; #define LAS __attribute__((address_space(3)))
; __device__ __forceinline__ float shx(float v, int lane, int o) { return __builtin_bit_cast(float, __builtin_amdgcn_ds_bpermute((lane ^ o) << 2, __builtin_bit_cast(int, v))); }
; template <int TYPE> ...
;     ...
;     asm volatile("s_waitcnt lgkmcnt(0)" ::: "memory");
;     __builtin_amdgcn_s_barrier();
;     asm volatile("" ::: "memory");
;     ...
;     float inv_l = 1.f;
;     if (TYPE != 1) { const float lt = l_run + shx(l_run, lane, 32); inv_l = 1.0f / lt; }
;     float ssq = 0.f;
; #pragma unroll
;     for (int d = 0; d < NDB; ++d)
; #pragma unroll
;         for (int r = 0; r < 16; ++r) { o[d][r] *= inv_l; ssq += o[d][r] * o[d][r]; }
;     ssq += shx(ssq, lane, 32);
;     const float rinv = 1.0f / sqrtf(ssq * (1.0f / DV) + EPS);
;     constexpr int ROWB = DV * 2 + 16, CH = DV / 8;
;     LAS unsigned char* stg_ = lds + wid * (32 * ROWB);
;     const float* gp = gout + COLOFF + h * DV + 4 * hi;
.LBB0_521:
	ds_bpermute_b32 v0, v171, v172
	s_mulk_i32 s3, 0x2200
	s_waitcnt lgkmcnt(0)
	s_barrier
	s_waitcnt lgkmcnt(0)
	v_add_f32_e32 v0, v172, v0
	v_div_scale_f32 v2, s[0:1], v0, v0, 1.0
	v_rcp_f32_e32 v3, v2
	v_div_scale_f32 v4, vcc, 1.0, v0, 1.0
	s_add_i32 s0, s3, 0
	v_fma_f32 v5, -v2, v3, 1.0
	v_fmac_f32_e32 v3, v5, v3
	v_mul_f32_e32 v5, v4, v3
	v_fma_f32 v6, -v2, v5, v4
	v_fmac_f32_e32 v5, v6, v3
	v_fma_f32 v2, -v2, v5, v4
	v_div_fmas_f32 v2, v2, v3, v5
	v_div_fixup_f32 v0, v2, v0, 1.0
	v_pk_mul_f32 v[86:87], v[64:65], v[0:1] op_sel_hi:[1,0]
	v_pk_mul_f32 v[82:83], v[66:67], v[0:1] op_sel_hi:[1,0]
	v_pk_mul_f32 v[102:103], v[86:87], v[86:87]
	v_pk_mul_f32 v[14:15], v[26:27], v[0:1] op_sel_hi:[1,0]
	v_pk_mul_f32 v[80:81], v[28:29], v[0:1] op_sel_hi:[1,0]
	v_pk_mul_f32 v[30:31], v[30:31], v[0:1] op_sel_hi:[1,0]
	v_pk_mul_f32 v[100:101], v[82:83], v[82:83]
	v_pk_mul_f32 v[84:85], v[70:71], v[0:1] op_sel_hi:[1,0]
	v_pk_mul_f32 v[90:91], v[68:69], v[0:1] op_sel_hi:[1,0]
	v_pk_mul_f32 v[88:89], v[74:75], v[0:1] op_sel_hi:[1,0]
	v_pk_mul_f32 v[92:93], v[72:73], v[0:1] op_sel_hi:[1,0]
	v_pk_mul_f32 v[72:73], v[78:79], v[0:1] op_sel_hi:[1,0]
	v_pk_mul_f32 v[74:75], v[76:77], v[0:1] op_sel_hi:[1,0]
	v_pk_mul_f32 v[50:51], v[50:51], v[0:1] op_sel_hi:[1,0]
	v_pk_mul_f32 v[76:77], v[48:49], v[0:1] op_sel_hi:[1,0]
	v_pk_mul_f32 v[48:49], v[54:55], v[0:1] op_sel_hi:[1,0]
	v_pk_mul_f32 v[54:55], v[52:53], v[0:1] op_sel_hi:[1,0]
	v_pk_mul_f32 v[52:53], v[58:59], v[0:1] op_sel_hi:[1,0]
	v_pk_mul_f32 v[58:59], v[56:57], v[0:1] op_sel_hi:[1,0]
	v_pk_mul_f32 v[56:57], v[62:63], v[0:1] op_sel_hi:[1,0]
	v_pk_mul_f32 v[60:61], v[60:61], v[0:1] op_sel_hi:[1,0]
	v_pk_mul_f32 v[34:35], v[34:35], v[0:1] op_sel_hi:[1,0]
	v_pk_mul_f32 v[62:63], v[32:33], v[0:1] op_sel_hi:[1,0]
	v_pk_mul_f32 v[32:33], v[38:39], v[0:1] op_sel_hi:[1,0]
	v_pk_mul_f32 v[38:39], v[36:37], v[0:1] op_sel_hi:[1,0]
	v_pk_mul_f32 v[36:37], v[42:43], v[0:1] op_sel_hi:[1,0]
	v_pk_mul_f32 v[42:43], v[40:41], v[0:1] op_sel_hi:[1,0]
	v_pk_mul_f32 v[40:41], v[46:47], v[0:1] op_sel_hi:[1,0]
	v_pk_mul_f32 v[44:45], v[44:45], v[0:1] op_sel_hi:[1,0]
	v_pk_mul_f32 v[18:19], v[18:19], v[0:1] op_sel_hi:[1,0]
	v_pk_mul_f32 v[46:47], v[16:17], v[0:1] op_sel_hi:[1,0]
	v_pk_mul_f32 v[16:17], v[22:23], v[0:1] op_sel_hi:[1,0]
	v_pk_mul_f32 v[20:21], v[20:21], v[0:1] op_sel_hi:[1,0]
	v_pk_mul_f32 v[22:23], v[24:25], v[0:1] op_sel_hi:[1,0]
	v_add_f32_e32 v0, v102, v103
	v_add_f32_e32 v0, v100, v0
	v_pk_mul_f32 v[106:107], v[90:91], v[90:91]
	v_add_f32_e32 v0, v101, v0
	v_add_f32_e32 v0, v106, v0
	v_pk_mul_f32 v[104:105], v[84:85], v[84:85]
	v_add_f32_e32 v0, v107, v0
	v_add_f32_e32 v0, v104, v0
	v_pk_mul_f32 v[110:111], v[92:93], v[92:93]
	v_add_f32_e32 v0, v105, v0
	v_add_f32_e32 v0, v110, v0
	v_pk_mul_f32 v[108:109], v[88:89], v[88:89]
	v_add_f32_e32 v0, v111, v0
	v_add_f32_e32 v0, v108, v0
	v_pk_mul_f32 v[112:113], v[74:75], v[74:75]
	v_add_f32_e32 v0, v109, v0
	v_add_f32_e32 v0, v112, v0
	v_pk_mul_f32 v[78:79], v[72:73], v[72:73]
	v_add_f32_e32 v0, v113, v0
	v_add_f32_e32 v0, v78, v0
	v_pk_mul_f32 v[116:117], v[76:77], v[76:77]
	v_add_f32_e32 v0, v79, v0
	v_add_f32_e32 v0, v116, v0
	v_pk_mul_f32 v[114:115], v[50:51], v[50:51]
	v_add_f32_e32 v0, v117, v0
	s_lshl_b32 s1, s8, 2
	v_readlane_b32 s3, v254, 53
	v_add_f32_e32 v0, v114, v0
	s_add_u32 s6, s3, s1
	v_readlane_b32 s1, v254, 55
	v_pk_mul_f32 v[120:121], v[54:55], v[54:55]
	v_add_f32_e32 v0, v115, v0
	s_addc_u32 s7, s1, 0
	v_add_f32_e32 v0, v120, v0
	global_load_dwordx4 v[64:67], v160, s[6:7]
	global_load_dwordx4 v[26:29], v160, s[6:7] offset:32
	v_pk_mul_f32 v[118:119], v[48:49], v[48:49]
	v_add_f32_e32 v0, v121, v0
	v_add_f32_e32 v0, v118, v0
	v_pk_mul_f32 v[124:125], v[58:59], v[58:59]
	v_add_f32_e32 v0, v119, v0
	v_add_f32_e32 v0, v124, v0
	v_pk_mul_f32 v[122:123], v[52:53], v[52:53]
	v_add_f32_e32 v0, v125, v0
	v_add_f32_e32 v0, v122, v0
	v_pk_mul_f32 v[128:129], v[60:61], v[60:61]
	v_add_f32_e32 v0, v123, v0
	global_load_dwordx4 v[68:71], v160, s[6:7] offset:64
	global_load_dwordx4 v[2:5], v160, s[6:7] offset:96
	v_add_f32_e32 v0, v128, v0
	v_pk_mul_f32 v[126:127], v[56:57], v[56:57]
	v_add_f32_e32 v0, v129, v0
	v_add_f32_e32 v0, v126, v0
	v_pk_mul_f32 v[132:133], v[62:63], v[62:63]
	v_add_f32_e32 v0, v127, v0
	v_add_f32_e32 v0, v132, v0
	v_pk_mul_f32 v[130:131], v[34:35], v[34:35]
	v_add_f32_e32 v0, v133, v0
	v_add_f32_e32 v0, v130, v0
	v_pk_mul_f32 v[136:137], v[38:39], v[38:39]
	v_add_f32_e32 v0, v131, v0
	v_add_f32_e32 v0, v136, v0
	v_pk_mul_f32 v[134:135], v[32:33], v[32:33]
	v_add_f32_e32 v0, v137, v0
	v_add_f32_e32 v0, v134, v0
	v_pk_mul_f32 v[140:141], v[42:43], v[42:43]
	v_add_f32_e32 v0, v135, v0
	v_add_f32_e32 v0, v140, v0
	v_pk_mul_f32 v[138:139], v[36:37], v[36:37]
	v_add_f32_e32 v0, v141, v0
	v_add_f32_e32 v0, v138, v0
	v_pk_mul_f32 v[144:145], v[44:45], v[44:45]
	v_add_f32_e32 v0, v139, v0
	v_add_f32_e32 v0, v144, v0
	v_pk_mul_f32 v[142:143], v[40:41], v[40:41]
	v_add_f32_e32 v0, v145, v0
	v_add_f32_e32 v0, v142, v0
	v_pk_mul_f32 v[148:149], v[46:47], v[46:47]
	v_add_f32_e32 v0, v143, v0
	v_add_f32_e32 v0, v148, v0
	v_pk_mul_f32 v[146:147], v[18:19], v[18:19]
	v_add_f32_e32 v0, v149, v0
	v_add_f32_e32 v0, v146, v0
	v_pk_mul_f32 v[152:153], v[20:21], v[20:21]
	v_add_f32_e32 v0, v147, v0
	v_add_f32_e32 v0, v152, v0
	v_pk_mul_f32 v[150:151], v[16:17], v[16:17]
	v_add_f32_e32 v0, v153, v0
	v_add_f32_e32 v0, v150, v0
	v_pk_mul_f32 v[24:25], v[22:23], v[22:23]
	v_add_f32_e32 v0, v151, v0
	v_add_f32_e32 v0, v24, v0
	v_pk_mul_f32 v[94:95], v[14:15], v[14:15]
	v_add_f32_e32 v0, v25, v0
	v_add_f32_e32 v0, v94, v0
	v_pk_mul_f32 v[96:97], v[80:81], v[80:81]
	v_add_f32_e32 v0, v95, v0
	v_add_f32_e32 v0, v96, v0
	v_pk_mul_f32 v[98:99], v[30:31], v[30:31]
	v_add_f32_e32 v0, v97, v0
	v_add_f32_e32 v0, v98, v0
	v_add_f32_e32 v0, v99, v0
	ds_bpermute_b32 v24, v171, v0
	v_mul_u32_u24_e32 v25, 0x110, v169
	v_add3_u32 v78, s0, v25, v170
	global_load_dwordx4 v[10:13], v160, s[6:7] offset:128
	global_load_dwordx4 v[6:9], v160, s[6:7] offset:160
	global_load_dwordx4 v[94:97], v160, s[6:7] offset:192
	global_load_dwordx4 v[98:101], v160, s[6:7] offset:224
	s_waitcnt lgkmcnt(0)
; #define LAS __attribute__((address_space(3)))
; __device__ __forceinline__ unsigned cvt_pk_bf16(float lo, float hi) { const f32x2 v = {lo, hi}; const bf16x2_t b = __builtin_convertvector(v, bf16x2_t); return __builtin_bit_cast(unsigned, b); }
; __device__ __forceinline__ float shx(float v, int lane, int o) { return __builtin_bit_cast(float, __builtin_amdgcn_ds_bpermute((lane ^ o) << 2, __builtin_bit_cast(int, v))); }
; template <int TYPE> ...
;     ...
;     ssq += shx(ssq, lane, 32);
;     const float rinv = 1.0f / sqrtf(ssq * (1.0f / DV) + EPS);
;     constexpr int ROWB = DV * 2 + 16, CH = DV / 8;
;     LAS unsigned char* stg_ = lds + wid * (32 * ROWB);
;     const float* gp = gout + COLOFF + h * DV + 4 * hi;
; #pragma unroll
;     for (int d = 0; d < NDB; ++d)
; #pragma unroll
;         for (int rg = 0; rg < 4; ++rg) {
;             const f32x4 g4 = *(const f32x4*)(gp + 32 * d + 8 * rg);
;             u32x2 w; w.x = cvt_pk_bf16(o[d][4 * rg] * rinv * g4[0], o[d][4 * rg + 1] * rinv * g4[1]); w.y = cvt_pk_bf16(o[d][4 * rg + 2] * rinv * g4[2], o[d][4 * rg + 3] * rinv * g4[3]);
;             *(LAS u32x2*)(stg_ + r32 * ROWB + (32 * d + 8 * rg + 4 * hi) * 2) = w;
;         }
	v_add_f32_e32 v0, v0, v24
	v_fmamk_f32 v0, v0, 0x3c000000, v241
	v_mul_f32_e32 v24, 0x4f800000, v0
	v_cmp_gt_f32_e32 vcc, s85, v0
	global_load_dwordx4 v[102:105], v160, s[6:7] offset:256
	global_load_dwordx4 v[106:109], v160, s[6:7] offset:288
	global_load_dwordx4 v[110:113], v160, s[6:7] offset:320
	global_load_dwordx4 v[114:117], v160, s[6:7] offset:352
	v_cndmask_b32_e32 v0, v0, v24, vcc
	v_sqrt_f32_e32 v24, v0
	global_load_dwordx4 v[118:121], v160, s[6:7] offset:384
	global_load_dwordx4 v[122:125], v160, s[6:7] offset:416
	global_load_dwordx4 v[126:129], v160, s[6:7] offset:448
	s_ashr_i32 s3, s2, 31
	s_lshl_b64 s[2:3], s[2:3], 12
	v_add_u32_e32 v25, -1, v24
	v_fma_f32 v79, -v25, v24, v0
	v_cmp_ge_f32_e64 s[4:5], 0, v79
	v_add_u32_e32 v79, 1, v24
	v_readlane_b32 s1, v253, 41
	v_cndmask_b32_e64 v25, v24, v25, s[4:5]
	v_fma_f32 v24, -v79, v24, v0
	v_cmp_lt_f32_e64 s[4:5], 0, v24
	s_add_u32 s1, s1, s2
	v_readlane_b32 s2, v253, 42
	v_cndmask_b32_e64 v24, v25, v79, s[4:5]
	v_mul_f32_e32 v25, 0x37800000, v24
	v_cndmask_b32_e32 v24, v24, v25, vcc
	v_cmp_class_f32_e32 vcc, v0, v242
	s_addc_u32 s3, s2, s3
	s_lshl_b32 s2, s8, 1
	v_cndmask_b32_e32 v0, v24, v0, vcc
	v_div_scale_f32 v24, s[4:5], v0, v0, 1.0
	v_rcp_f32_e32 v25, v24
	s_add_u32 s2, s1, s2
	s_addc_u32 s3, s3, 0
	v_fma_f32 v79, -v24, v25, 1.0
	v_fmac_f32_e32 v25, v79, v25
	v_div_scale_f32 v79, vcc, 1.0, v0, 1.0
	v_mul_f32_e32 v130, v79, v25
	v_fma_f32 v131, -v24, v130, v79
	v_fmac_f32_e32 v130, v131, v25
	v_fma_f32 v24, -v24, v130, v79
	v_div_fmas_f32 v24, v24, v25, v130
	v_div_fixup_f32 v0, v24, v0, 1.0
	v_pk_mul_f32 v[24:25], v[86:87], v[0:1] op_sel_hi:[1,0]
	s_waitcnt vmcnt(0)
	v_pk_mul_f32 v[24:25], v[64:65], v[24:25]
	v_pk_mul_f32 v[64:65], v[82:83], v[0:1] op_sel_hi:[1,0]
	v_cvt_pk_bf16_f32 v24, v24, v25
	v_pk_mul_f32 v[64:65], v[66:67], v[64:65]
	s_nop 0
	v_cvt_pk_bf16_f32 v25, v64, v65
	v_pk_mul_f32 v[64:65], v[90:91], v[0:1] op_sel_hi:[1,0]
	s_nop 0
	v_pk_mul_f32 v[26:27], v[26:27], v[64:65]
	v_pk_mul_f32 v[64:65], v[84:85], v[0:1] op_sel_hi:[1,0]
	v_cvt_pk_bf16_f32 v26, v26, v27
	v_pk_mul_f32 v[28:29], v[28:29], v[64:65]
	v_pk_mul_f32 v[64:65], v[74:75], v[0:1] op_sel_hi:[1,0]
	v_cvt_pk_bf16_f32 v27, v28, v29
	ds_write2_b64 v78, v[24:25], v[26:27] offset1:2
	v_pk_mul_f32 v[24:25], v[92:93], v[0:1] op_sel_hi:[1,0]
	v_pk_mul_f32 v[2:3], v[2:3], v[64:65]
	v_pk_mul_f32 v[24:25], v[68:69], v[24:25]
	v_pk_mul_f32 v[64:65], v[72:73], v[0:1] op_sel_hi:[1,0]
	v_cvt_pk_bf16_f32 v28, v24, v25
	v_pk_mul_f32 v[24:25], v[88:89], v[0:1] op_sel_hi:[1,0]
	v_pk_mul_f32 v[4:5], v[4:5], v[64:65]
	v_pk_mul_f32 v[24:25], v[70:71], v[24:25]
	v_cvt_pk_bf16_f32 v2, v2, v3
	v_cvt_pk_bf16_f32 v29, v24, v25
	global_load_dwordx4 v[24:27], v160, s[6:7] offset:480
	v_cvt_pk_bf16_f32 v3, v4, v5
	ds_write2_b64 v78, v[28:29], v[2:3] offset0:4 offset1:6
	v_pk_mul_f32 v[2:3], v[76:77], v[0:1] op_sel_hi:[1,0]
	v_pk_mul_f32 v[4:5], v[50:51], v[0:1] op_sel_hi:[1,0]
	v_pk_mul_f32 v[2:3], v[10:11], v[2:3]
	v_pk_mul_f32 v[4:5], v[12:13], v[4:5]
	v_cvt_pk_bf16_f32 v2, v2, v3
	v_cvt_pk_bf16_f32 v3, v4, v5
	v_pk_mul_f32 v[4:5], v[54:55], v[0:1] op_sel_hi:[1,0]
	s_nop 0
	v_pk_mul_f32 v[4:5], v[6:7], v[4:5]
	v_pk_mul_f32 v[6:7], v[48:49], v[0:1] op_sel_hi:[1,0]
	v_cvt_pk_bf16_f32 v4, v4, v5
	v_pk_mul_f32 v[6:7], v[8:9], v[6:7]
	s_nop 0
	v_cvt_pk_bf16_f32 v5, v6, v7
	ds_write2_b64 v78, v[2:3], v[4:5] offset0:8 offset1:10
	v_pk_mul_f32 v[2:3], v[58:59], v[0:1] op_sel_hi:[1,0]
	v_pk_mul_f32 v[4:5], v[52:53], v[0:1] op_sel_hi:[1,0]
	v_pk_mul_f32 v[2:3], v[94:95], v[2:3]
	v_pk_mul_f32 v[4:5], v[96:97], v[4:5]
	v_cvt_pk_bf16_f32 v2, v2, v3
	v_cvt_pk_bf16_f32 v3, v4, v5
	v_pk_mul_f32 v[4:5], v[60:61], v[0:1] op_sel_hi:[1,0]
	v_pk_mul_f32 v[6:7], v[56:57], v[0:1] op_sel_hi:[1,0]
	v_pk_mul_f32 v[4:5], v[98:99], v[4:5]
	v_pk_mul_f32 v[6:7], v[100:101], v[6:7]
	v_cvt_pk_bf16_f32 v4, v4, v5
	v_cvt_pk_bf16_f32 v5, v6, v7
	ds_write2_b64 v78, v[2:3], v[4:5] offset0:12 offset1:14
	v_pk_mul_f32 v[2:3], v[62:63], v[0:1] op_sel_hi:[1,0]
	v_pk_mul_f32 v[4:5], v[34:35], v[0:1] op_sel_hi:[1,0]
	v_pk_mul_f32 v[2:3], v[102:103], v[2:3]
	v_pk_mul_f32 v[4:5], v[104:105], v[4:5]
	v_cvt_pk_bf16_f32 v2, v2, v3
	v_cvt_pk_bf16_f32 v3, v4, v5
	v_pk_mul_f32 v[4:5], v[38:39], v[0:1] op_sel_hi:[1,0]
	v_pk_mul_f32 v[6:7], v[32:33], v[0:1] op_sel_hi:[1,0]
	v_pk_mul_f32 v[4:5], v[106:107], v[4:5]
	v_pk_mul_f32 v[6:7], v[108:109], v[6:7]
	v_cvt_pk_bf16_f32 v4, v4, v5
	v_cvt_pk_bf16_f32 v5, v6, v7
	ds_write2_b64 v78, v[2:3], v[4:5] offset0:16 offset1:18
	v_pk_mul_f32 v[2:3], v[42:43], v[0:1] op_sel_hi:[1,0]
	v_pk_mul_f32 v[4:5], v[36:37], v[0:1] op_sel_hi:[1,0]
	v_pk_mul_f32 v[2:3], v[110:111], v[2:3]
	v_pk_mul_f32 v[4:5], v[112:113], v[4:5]
	v_cvt_pk_bf16_f32 v2, v2, v3
	v_cvt_pk_bf16_f32 v3, v4, v5
	v_pk_mul_f32 v[4:5], v[44:45], v[0:1] op_sel_hi:[1,0]
	v_pk_mul_f32 v[6:7], v[40:41], v[0:1] op_sel_hi:[1,0]
	v_pk_mul_f32 v[4:5], v[114:115], v[4:5]
	v_pk_mul_f32 v[6:7], v[116:117], v[6:7]
	v_cvt_pk_bf16_f32 v4, v4, v5
	v_cvt_pk_bf16_f32 v5, v6, v7
	ds_write2_b64 v78, v[2:3], v[4:5] offset0:20 offset1:22
	v_pk_mul_f32 v[2:3], v[46:47], v[0:1] op_sel_hi:[1,0]
	v_pk_mul_f32 v[4:5], v[18:19], v[0:1] op_sel_hi:[1,0]
	v_pk_mul_f32 v[2:3], v[118:119], v[2:3]
	v_pk_mul_f32 v[4:5], v[120:121], v[4:5]
	v_cvt_pk_bf16_f32 v2, v2, v3
	v_cvt_pk_bf16_f32 v3, v4, v5
	v_pk_mul_f32 v[4:5], v[20:21], v[0:1] op_sel_hi:[1,0]
	v_pk_mul_f32 v[6:7], v[16:17], v[0:1] op_sel_hi:[1,0]
	v_pk_mul_f32 v[4:5], v[122:123], v[4:5]
	v_pk_mul_f32 v[6:7], v[124:125], v[6:7]
	v_cvt_pk_bf16_f32 v4, v4, v5
	v_cvt_pk_bf16_f32 v5, v6, v7
	ds_write2_b64 v78, v[2:3], v[4:5] offset0:24 offset1:26
	v_pk_mul_f32 v[2:3], v[22:23], v[0:1] op_sel_hi:[1,0]
	v_pk_mul_f32 v[4:5], v[14:15], v[0:1] op_sel_hi:[1,0]
	v_pk_mul_f32 v[2:3], v[126:127], v[2:3]
	v_pk_mul_f32 v[4:5], v[128:129], v[4:5]
	v_cvt_pk_bf16_f32 v2, v2, v3
	v_cvt_pk_bf16_f32 v3, v4, v5
	v_pk_mul_f32 v[4:5], v[80:81], v[0:1] op_sel_hi:[1,0]
	v_pk_mul_f32 v[6:7], v[30:31], v[0:1] op_sel_hi:[1,0]
	s_waitcnt vmcnt(0)
; #define LAS __attribute__((address_space(3)))
; template <int TYPE> ...
;     ...
;     asm volatile("s_waitcnt lgkmcnt(0)" ::: "memory");
;     bf16_t* ob = OB + (size_t)(rowbase + q0w) * DM + COLOFF + h * DV;
; #pragma unroll
;     for (int i = 0; i < CH / 2; ++i) {
;         const int row = i * (64 / CH) + lane / CH, ch = lane % CH;
;         const u32x4 v = *(const LAS u32x4*)(stg_ + row * ROWB + ch * 16);
;         *(u32x4*)(ob + (size_t)row * DM + ch * 8) = v;
;     }
	v_pk_mul_f32 v[4:5], v[24:25], v[4:5]
	v_pk_mul_f32 v[6:7], v[26:27], v[6:7]
	v_cvt_pk_bf16_f32 v4, v4, v5
	v_cvt_pk_bf16_f32 v5, v6, v7
	ds_write2_b64 v78, v[2:3], v[4:5] offset0:28 offset1:30
	v_lshlrev_b32_e32 v0, 4, v168
	v_mul_u32_u24_e32 v2, 0x110, v161
	s_waitcnt lgkmcnt(0)
	v_add3_u32 v14, s0, v0, v2
	ds_read_b128 v[4:7], v14
	ds_read_b128 v[8:11], v14 offset:1088
	v_lshl_add_u64 v[2:3], s[2:3], 0, v[0:1]
	v_lshlrev_b32_e32 v0, 12, v161
	v_lshl_add_u64 v[12:13], v[2:3], 0, v[0:1]
	s_waitcnt lgkmcnt(1)
	global_store_dwordx4 v[12:13], v[4:7], off sc1
	s_nop 1
	v_or_b32_e32 v4, 0x4000, v0
	v_mov_b32_e32 v5, v1
	v_lshl_add_u64 v[4:5], v[2:3], 0, v[4:5]
	s_waitcnt lgkmcnt(0)
	global_store_dwordx4 v[4:5], v[8:11], off sc1
	ds_read_b128 v[4:7], v14 offset:2176
	s_nop 0
	v_or_b32_e32 v8, 0x8000, v0
	v_mov_b32_e32 v9, v1
	v_lshl_add_u64 v[12:13], v[2:3], 0, v[8:9]
	ds_read_b128 v[8:11], v14 offset:3264
	s_waitcnt lgkmcnt(1)
	global_store_dwordx4 v[12:13], v[4:7], off sc1
	s_nop 1
	v_or_b32_e32 v4, 0xc000, v0
	v_mov_b32_e32 v5, v1
	v_lshl_add_u64 v[4:5], v[2:3], 0, v[4:5]
	s_waitcnt lgkmcnt(0)
	global_store_dwordx4 v[4:5], v[8:11], off sc1
	ds_read_b128 v[4:7], v14 offset:4352
	s_nop 0
	v_or_b32_e32 v8, 0x10000, v0
	v_mov_b32_e32 v9, v1
	v_lshl_add_u64 v[12:13], v[2:3], 0, v[8:9]
	ds_read_b128 v[8:11], v14 offset:5440
	s_waitcnt lgkmcnt(1)
	global_store_dwordx4 v[12:13], v[4:7], off sc1
	ds_read_b128 v[4:7], v14 offset:6528
	v_or_b32_e32 v12, 0x14000, v0
	v_mov_b32_e32 v13, v1
	v_lshl_add_u64 v[12:13], v[2:3], 0, v[12:13]
	v_or_b32_e32 v0, 0x18000, v0
	s_waitcnt lgkmcnt(1)
	global_store_dwordx4 v[12:13], v[8:11], off sc1
	s_nop 1
	v_lshl_add_u64 v[8:9], v[2:3], 0, v[0:1]
	s_waitcnt lgkmcnt(0)
	global_store_dwordx4 v[8:9], v[4:7], off sc1
	v_add_u32_e32 v0, 0x1dc0, v14
	s_nop 0
	v_or_b32_e32 v4, 28, v161
.LBB0_522:
	ds_read_b128 v[6:9], v0
	v_lshlrev_b32_e32 v0, 12, v4
	v_readlane_b32 s8, v254, 59
	s_waitcnt lgkmcnt(0)
	v_lshl_add_u64 v[2:3], v[2:3], 0, v[0:1]
	s_add_i32 s8, s8, 1
	global_store_dwordx4 v[2:3], v[6:9], off sc1
	s_mov_b64 s[2:3], 0

; #define LAS __attribute__((address_space(3)))
; __device__ __forceinline__ unsigned cvt_pk_bf16(float lo, float hi) { const f32x2 v = {lo, hi}; const bf16x2_t b = __builtin_convertvector(v, bf16x2_t); return __builtin_bit_cast(unsigned, b); }
; __device__ __forceinline__ float shx(float v, int lane, int o) { return __builtin_bit_cast(float, __builtin_amdgcn_ds_bpermute((lane ^ o) << 2, __builtin_bit_cast(int, v))); }
; template <int TYPE> ...
;     ...
;     if (TYPE != 1) { const float lt = l_run + shx(l_run, lane, 32); inv_l = 1.0f / lt; }
;     float ssq = 0.f;
; #pragma unroll
;     for (int d = 0; d < NDB; ++d)
; #pragma unroll
;         for (int r = 0; r < 16; ++r) { o[d][r] *= inv_l; ssq += o[d][r] * o[d][r]; }
;     ssq += shx(ssq, lane, 32);
;     const float rinv = 1.0f / sqrtf(ssq * (1.0f / DV) + EPS);
;     constexpr int ROWB = DV * 2 + 16, CH = DV / 8;
;     LAS unsigned char* stg_ = lds + wid * (32 * ROWB);
;     const float* gp = gout + COLOFF + h * DV + 4 * hi;
; #pragma unroll
;     for (int d = 0; d < NDB; ++d)
; #pragma unroll
;         for (int rg = 0; rg < 4; ++rg) {
;             const f32x4 g4 = *(const f32x4*)(gp + 32 * d + 8 * rg);
;             u32x2 w; w.x = cvt_pk_bf16(o[d][4 * rg] * rinv * g4[0], o[d][4 * rg + 1] * rinv * g4[1]); w.y = cvt_pk_bf16(o[d][4 * rg + 2] * rinv * g4[2], o[d][4 * rg + 3] * rinv * g4[3]);
;             *(LAS u32x2*)(stg_ + r32 * ROWB + (32 * d + 8 * rg + 4 * hi) * 2) = w;
;         }
;     asm volatile("s_waitcnt lgkmcnt(0)" ::: "memory");
;     bf16_t* ob = OB + (size_t)(rowbase + q0w) * DM + COLOFF + h * DV;
; #pragma unroll
;     for (int i = 0; i < CH / 2; ++i) {
;         const int row = i * (64 / CH) + lane / CH, ch = lane % CH;
;         const u32x4 v = *(const LAS u32x4*)(stg_ + row * ROWB + ch * 16);
;         *(u32x4*)(ob + (size_t)row * DM + ch * 8) = v;
;     }
.LBB0_647:
	s_nop 9
	v_mul_f32_e32 v0, v19, v19
	v_fmac_f32_e32 v0, v18, v18
	v_fmac_f32_e32 v0, v20, v20
	v_fmac_f32_e32 v0, v21, v21
	v_fmac_f32_e32 v0, v22, v22
	v_fmac_f32_e32 v0, v23, v23
	v_fmac_f32_e32 v0, v24, v24
	v_fmac_f32_e32 v0, v25, v25
	v_fmac_f32_e32 v0, v26, v26
	v_fmac_f32_e32 v0, v27, v27
	v_fmac_f32_e32 v0, v28, v28
	v_fmac_f32_e32 v0, v29, v29
	v_fmac_f32_e32 v0, v30, v30
	v_fmac_f32_e32 v0, v31, v31
	v_fmac_f32_e32 v0, v32, v32
	v_fmac_f32_e32 v0, v33, v33
	v_fmac_f32_e32 v0, v2, v2
	v_fmac_f32_e32 v0, v3, v3
	v_fmac_f32_e32 v0, v4, v4
	v_fmac_f32_e32 v0, v5, v5
	v_fmac_f32_e32 v0, v6, v6
	v_fmac_f32_e32 v0, v7, v7
	v_fmac_f32_e32 v0, v8, v8
	v_fmac_f32_e32 v0, v9, v9
	v_fmac_f32_e32 v0, v10, v10
	v_fmac_f32_e32 v0, v11, v11
	v_pk_mul_f32 v[38:39], v[12:13], v[12:13]
	v_pk_mul_f32 v[36:37], v[14:15], v[14:15]
	v_add_f32_e32 v0, v38, v0
	v_add_f32_e32 v0, v39, v0
	v_add_f32_e32 v0, v36, v0
	v_pk_mul_f32 v[34:35], v[16:17], v[16:17]
	v_add_f32_e32 v0, v37, v0
	v_add_f32_e32 v0, v34, v0
	v_add_f32_e32 v0, v35, v0
	ds_bpermute_b32 v34, v133, v0
	v_readlane_b32 s1, v254, 63
	s_mulk_i32 s1, 0x1200
	v_readlane_b32 s12, v255, 4
	s_add_i32 s1, s1, 0
	s_waitcnt lgkmcnt(0)
	v_add_f32_e32 v0, v0, v34
	v_fmamk_f32 v0, v0, 0x3c800000, v241
	v_cmp_gt_f32_e32 vcc, s85, v0
	v_mul_f32_e32 v34, 0x4f800000, v0
	s_waitcnt lgkmcnt(0)
	s_barrier
	v_cndmask_b32_e32 v0, v0, v34, vcc
	v_sqrt_f32_e32 v34, v0
	v_lshlrev_b32_e32 v40, 2, v132
	v_mul_u32_u24_e32 v41, 0x90, v130
	v_add_u32_e32 v35, -1, v34
	v_fma_f32 v36, -v35, v34, v0
	v_cmp_ge_f32_e64 s[4:5], 0, v36
	v_add_u32_e32 v36, 1, v34
	s_nop 0
	v_cndmask_b32_e64 v35, v34, v35, s[4:5]
	v_fma_f32 v34, -v36, v34, v0
	v_cmp_lt_f32_e64 s[4:5], 0, v34
	s_nop 1
	v_cndmask_b32_e64 v34, v35, v36, s[4:5]
	v_mul_f32_e32 v35, 0x37800000, v34
	v_cndmask_b32_e32 v34, v34, v35, vcc
	v_cmp_class_f32_e32 vcc, v0, v242
	s_nop 1
	v_cndmask_b32_e32 v0, v34, v0, vcc
	v_div_scale_f32 v34, s[2:3], v0, v0, 1.0
	v_rcp_f32_e32 v35, v34
	s_lshl_b32 s2, s12, 2
	v_readlane_b32 s3, v254, 54
	s_add_u32 s4, s3, s2
	v_fma_f32 v36, -v34, v35, 1.0
	v_fmac_f32_e32 v35, v36, v35
	v_div_scale_f32 v36, vcc, 1.0, v0, 1.0
	v_mul_f32_e32 v37, v36, v35
	v_fma_f32 v38, -v34, v37, v36
	v_fmac_f32_e32 v37, v38, v35
	v_fma_f32 v34, -v34, v37, v36
	v_readlane_b32 s2, v254, 56
	v_div_fmas_f32 v34, v34, v35, v37
	s_addc_u32 s5, s2, 0
	v_div_fixup_f32 v0, v34, v0, 1.0
	global_load_dwordx4 v[34:37], v40, s[4:5]
	v_pk_mul_f32 v[18:19], v[18:19], v[0:1] op_sel_hi:[1,0]
	v_pk_mul_f32 v[2:3], v[2:3], v[0:1] op_sel_hi:[1,0]
	v_pk_mul_f32 v[6:7], v[6:7], v[0:1] op_sel_hi:[1,0]
	v_readlane_b32 s2, v254, 61
	v_readlane_b32 s3, v254, 62
	s_ashr_i32 s3, s2, 31
	s_lshl_b64 s[2:3], s[2:3], 12
	s_waitcnt vmcnt(0)
	v_pk_mul_f32 v[18:19], v[34:35], v[18:19]
	s_nop 0
	v_cvt_pk_bf16_f32 v38, v18, v19
	v_pk_mul_f32 v[18:19], v[20:21], v[0:1] op_sel_hi:[1,0]
	v_pk_mul_f32 v[20:21], v[22:23], v[0:1] op_sel_hi:[1,0]
	v_pk_mul_f32 v[18:19], v[36:37], v[18:19]
	global_load_dwordx4 v[34:37], v40, s[4:5] offset:32
	v_pk_mul_f32 v[22:23], v[24:25], v[0:1] op_sel_hi:[1,0]
	v_cvt_pk_bf16_f32 v39, v18, v19
	v_add3_u32 v18, s1, v41, v131
	v_pk_mul_f32 v[24:25], v[26:27], v[0:1] op_sel_hi:[1,0]
	v_pk_mul_f32 v[26:27], v[30:31], v[0:1] op_sel_hi:[1,0]
	s_waitcnt vmcnt(0)
	v_pk_mul_f32 v[20:21], v[34:35], v[20:21]
	v_pk_mul_f32 v[22:23], v[36:37], v[22:23]
	v_cvt_pk_bf16_f32 v20, v20, v21
	v_cvt_pk_bf16_f32 v21, v22, v23
	ds_write2_b64 v18, v[38:39], v[20:21] offset1:2
	global_load_dwordx4 v[20:23], v40, s[4:5] offset:64
	s_waitcnt vmcnt(0)
	v_pk_mul_f32 v[20:21], v[20:21], v[24:25]
	s_nop 0
	v_cvt_pk_bf16_f32 v24, v20, v21
	v_pk_mul_f32 v[20:21], v[28:29], v[0:1] op_sel_hi:[1,0]
	s_nop 0
	v_pk_mul_f32 v[20:21], v[22:23], v[20:21]
	s_nop 0
	v_cvt_pk_bf16_f32 v25, v20, v21
	global_load_dwordx4 v[20:23], v40, s[4:5] offset:96
	s_waitcnt vmcnt(0)
	v_pk_mul_f32 v[20:21], v[26:27], v[20:21]
	v_pk_mul_f32 v[26:27], v[32:33], v[0:1] op_sel_hi:[1,0]
	v_cvt_pk_bf16_f32 v20, v20, v21
	v_pk_mul_f32 v[22:23], v[26:27], v[22:23]
	s_nop 0
	v_cvt_pk_bf16_f32 v21, v22, v23
	ds_write2_b64 v18, v[24:25], v[20:21] offset0:4 offset1:6
	global_load_dwordx4 v[20:23], v40, s[4:5] offset:128
	s_waitcnt vmcnt(0)
	v_pk_mul_f32 v[2:3], v[2:3], v[20:21]
	s_nop 0
	v_cvt_pk_bf16_f32 v20, v2, v3
	v_pk_mul_f32 v[2:3], v[4:5], v[0:1] op_sel_hi:[1,0]
	s_nop 0
	v_pk_mul_f32 v[2:3], v[2:3], v[22:23]
	s_nop 0
	v_cvt_pk_bf16_f32 v21, v2, v3
	global_load_dwordx4 v[2:5], v40, s[4:5] offset:160
	s_waitcnt vmcnt(0)
	v_pk_mul_f32 v[2:3], v[6:7], v[2:3]
	v_pk_mul_f32 v[6:7], v[8:9], v[0:1] op_sel_hi:[1,0]
	v_cvt_pk_bf16_f32 v2, v2, v3
	v_pk_mul_f32 v[4:5], v[6:7], v[4:5]
	v_pk_mul_f32 v[6:7], v[10:11], v[0:1] op_sel_hi:[1,0]
	v_cvt_pk_bf16_f32 v3, v4, v5
	ds_write2_b64 v18, v[20:21], v[2:3] offset0:8 offset1:10
	global_load_dwordx4 v[2:5], v40, s[4:5] offset:192
	v_pk_mul_f32 v[8:9], v[14:15], v[0:1] op_sel_hi:[1,0]
	v_lshrrev_b32_e32 v10, 3, v129
	s_waitcnt vmcnt(0)
	v_pk_mul_f32 v[2:3], v[6:7], v[2:3]
	s_nop 0
	v_cvt_pk_bf16_f32 v6, v2, v3
	v_pk_mul_f32 v[2:3], v[12:13], v[0:1] op_sel_hi:[1,0]
	s_nop 0
	v_pk_mul_f32 v[2:3], v[2:3], v[4:5]
	s_nop 0
	v_cvt_pk_bf16_f32 v7, v2, v3
	global_load_dwordx4 v[2:5], v40, s[4:5] offset:224
	v_readlane_b32 s4, v251, 41
	v_readlane_b32 s8, v251, 45
	v_readlane_b32 s9, v251, 46
	s_add_u32 s2, s8, s2
	s_addc_u32 s3, s9, s3
	s_lshl_b32 s4, s12, 1
	s_add_u32 s2, s2, s4
	s_addc_u32 s3, s3, 0
	v_readlane_b32 s5, v251, 42
	s_mov_b64 s[4:5], 0
	v_readlane_b32 s6, v251, 43
	v_readlane_b32 s7, v251, 44
	v_readlane_b32 s10, v251, 47
	v_readlane_b32 s11, v251, 48
	s_waitcnt vmcnt(0)
	v_pk_mul_f32 v[2:3], v[8:9], v[2:3]
	v_pk_mul_f32 v[8:9], v[16:17], v[0:1] op_sel_hi:[1,0]
	v_cvt_pk_bf16_f32 v2, v2, v3
	v_pk_mul_f32 v[4:5], v[8:9], v[4:5]
	v_lshlrev_b32_e32 v0, 4, v128
	v_cvt_pk_bf16_f32 v3, v4, v5
	ds_write2_b64 v18, v[6:7], v[2:3] offset0:12 offset1:14
	v_and_b32_e32 v0, 0x70, v0
	v_mul_u32_u24_e32 v4, 0x90, v10
	s_waitcnt lgkmcnt(0)
	v_add3_u32 v11, s1, v0, v4
	ds_read_b128 v[4:7], v11
	v_lshl_add_u64 v[2:3], s[2:3], 0, v[0:1]
	s_mov_b64 s[2:3], 0x15800800
	v_lshl_add_u64 v[2:3], v[2:3], 0, s[2:3]
	v_lshlrev_b32_e32 v0, 12, v10
	v_lshl_add_u64 v[8:9], v[2:3], 0, v[0:1]
	s_waitcnt lgkmcnt(0)
	global_store_dwordx4 v[8:9], v[4:7], off sc1
	ds_read_b128 v[4:7], v11 offset:1152
	v_or_b32_e32 v8, 0x8000, v0
	v_mov_b32_e32 v9, v1
	v_lshl_add_u64 v[8:9], v[2:3], 0, v[8:9]
	v_or_b32_e32 v0, 0x10000, v0
	s_waitcnt lgkmcnt(0)
	global_store_dwordx4 v[8:9], v[4:7], off sc1
	ds_read_b128 v[4:7], v11 offset:2304
	v_lshl_add_u64 v[8:9], v[2:3], 0, v[0:1]
	v_add_u32_e32 v0, 0xd80, v11
	s_waitcnt lgkmcnt(0)
	global_store_dwordx4 v[8:9], v[4:7], off sc1
	s_nop 1
	v_or_b32_e32 v4, 24, v10

; __device__ __forceinline__ float shx(float v, int lane, int o) { return __builtin_bit_cast(float, __builtin_amdgcn_ds_bpermute((lane ^ o) << 2, __builtin_bit_cast(int, v))); }
; template <int TYPE> ...
;     ...
;     float inv_l = 1.f;
;     if (TYPE != 1) { const float lt = l_run + shx(l_run, lane, 32); inv_l = 1.0f / lt; }
;     float ssq = 0.f;
; #pragma unroll
;     for (int d = 0; d < NDB; ++d)
; #pragma unroll
;         for (int r = 0; r < 16; ++r) { o[d][r] *= inv_l; ssq += o[d][r] * o[d][r]; }
;     ssq += shx(ssq, lane, 32);
;     const float rinv = 1.0f / sqrtf(ssq * (1.0f / DV) + EPS);
.LBB0_668:
	ds_bpermute_b32 v0, v104, v113
	s_mulk_i32 s3, 0xe00
	s_add_i32 s1, s1, s3
	s_lshl_b32 s3, s75, 2
	s_waitcnt lgkmcnt(0)
	s_waitcnt lgkmcnt(0)
	v_add_f32_e32 v0, v113, v0
	v_div_scale_f32 v2, s[4:5], v0, v0, 1.0
	v_rcp_f32_e32 v3, v2
	v_div_scale_f32 v4, vcc, 1.0, v0, 1.0
	v_readlane_b32 s4, v254, 51
	v_fma_f32 v5, -v2, v3, 1.0
	v_fmac_f32_e32 v3, v5, v3
	v_mul_f32_e32 v5, v4, v3
	v_fma_f32 v6, -v2, v5, v4
	v_fmac_f32_e32 v5, v6, v3
	v_fma_f32 v2, -v2, v5, v4
	v_div_fmas_f32 v2, v2, v3, v5
	v_div_fixup_f32 v0, v2, v0, 1.0
	v_pk_mul_f32 v[58:59], v[32:33], v[0:1] op_sel_hi:[1,0]
	v_pk_mul_f32 v[54:55], v[34:35], v[0:1] op_sel_hi:[1,0]
	v_pk_mul_f32 v[60:61], v[58:59], v[58:59]
	v_pk_mul_f32 v[2:3], v[26:27], v[0:1] op_sel_hi:[1,0]
	v_pk_mul_f32 v[4:5], v[28:29], v[0:1] op_sel_hi:[1,0]
	v_pk_mul_f32 v[6:7], v[30:31], v[0:1] op_sel_hi:[1,0]
	v_pk_mul_f32 v[56:57], v[54:55], v[54:55]
	v_pk_mul_f32 v[62:63], v[38:39], v[0:1] op_sel_hi:[1,0]
	v_pk_mul_f32 v[64:65], v[36:37], v[0:1] op_sel_hi:[1,0]
	v_pk_mul_f32 v[42:43], v[42:43], v[0:1] op_sel_hi:[1,0]
	v_pk_mul_f32 v[70:71], v[40:41], v[0:1] op_sel_hi:[1,0]
	v_pk_mul_f32 v[46:47], v[46:47], v[0:1] op_sel_hi:[1,0]
	v_pk_mul_f32 v[44:45], v[44:45], v[0:1] op_sel_hi:[1,0]
	v_pk_mul_f32 v[76:77], v[18:19], v[0:1] op_sel_hi:[1,0]
	v_pk_mul_f32 v[80:81], v[16:17], v[0:1] op_sel_hi:[1,0]
	v_pk_mul_f32 v[84:85], v[22:23], v[0:1] op_sel_hi:[1,0]
	v_pk_mul_f32 v[86:87], v[20:21], v[0:1] op_sel_hi:[1,0]
	v_pk_mul_f32 v[24:25], v[24:25], v[0:1] op_sel_hi:[1,0]
	v_add_f32_e32 v0, v60, v61
	v_add_f32_e32 v0, v56, v0
	v_pk_mul_f32 v[66:67], v[64:65], v[64:65]
	v_add_f32_e32 v0, v57, v0
	v_add_f32_e32 v0, v66, v0
	v_pk_mul_f32 v[38:39], v[62:63], v[62:63]
	v_add_f32_e32 v0, v67, v0
	v_add_f32_e32 v0, v38, v0
	v_pk_mul_f32 v[40:41], v[70:71], v[70:71]
	v_add_f32_e32 v0, v39, v0
	v_add_f32_e32 v0, v40, v0
	v_pk_mul_f32 v[68:69], v[42:43], v[42:43]
	v_add_f32_e32 v0, v41, v0
	v_add_f32_e32 v0, v68, v0
	v_pk_mul_f32 v[74:75], v[44:45], v[44:45]
	v_add_f32_e32 v0, v69, v0
	v_add_f32_e32 v0, v74, v0
	v_pk_mul_f32 v[72:73], v[46:47], v[46:47]
	v_add_f32_e32 v0, v75, v0
	v_add_f32_e32 v0, v72, v0
	v_pk_mul_f32 v[82:83], v[80:81], v[80:81]
	v_add_f32_e32 v0, v73, v0
	v_add_f32_e32 v0, v82, v0
	v_pk_mul_f32 v[78:79], v[76:77], v[76:77]
	v_add_f32_e32 v0, v83, v0
	v_add_f32_e32 v0, v78, v0
	v_pk_mul_f32 v[20:21], v[86:87], v[86:87]
	v_add_f32_e32 v0, v79, v0
	s_add_u32 s4, s4, s3
	v_readlane_b32 s3, v254, 52
	v_add_f32_e32 v0, v20, v0
	s_barrier
; #define LAS __attribute__((address_space(3)))
; __device__ __forceinline__ unsigned cvt_pk_bf16(float lo, float hi) { const f32x2 v = {lo, hi}; const bf16x2_t b = __builtin_convertvector(v, bf16x2_t); return __builtin_bit_cast(unsigned, b); }
; __device__ __forceinline__ float shx(float v, int lane, int o) { return __builtin_bit_cast(float, __builtin_amdgcn_ds_bpermute((lane ^ o) << 2, __builtin_bit_cast(int, v))); }
; template <int TYPE> ...
;     ...
;     ssq += shx(ssq, lane, 32);
;     const float rinv = 1.0f / sqrtf(ssq * (1.0f / DV) + EPS);
;     constexpr int ROWB = DV * 2 + 16, CH = DV / 8;
;     LAS unsigned char* stg_ = lds + wid * (32 * ROWB);
;     const float* gp = gout + COLOFF + h * DV + 4 * hi;
; #pragma unroll
;     for (int d = 0; d < NDB; ++d)
; #pragma unroll
;         for (int rg = 0; rg < 4; ++rg) {
;             const f32x4 g4 = *(const f32x4*)(gp + 32 * d + 8 * rg);
;             u32x2 w; w.x = cvt_pk_bf16(o[d][4 * rg] * rinv * g4[0], o[d][4 * rg + 1] * rinv * g4[1]); w.y = cvt_pk_bf16(o[d][4 * rg + 2] * rinv * g4[2], o[d][4 * rg + 3] * rinv * g4[3]);
;             *(LAS u32x2*)(stg_ + r32 * ROWB + (32 * d + 8 * rg + 4 * hi) * 2) = w;
;         }
;     asm volatile("s_waitcnt lgkmcnt(0)" ::: "memory");
;     bf16_t* ob = OB + (size_t)(rowbase + q0w) * DM + COLOFF + h * DV;
; #pragma unroll
;     for (int i = 0; i < CH / 2; ++i) {
;         const int row = i * (64 / CH) + lane / CH, ch = lane % CH;
;         const u32x4 v = *(const LAS u32x4*)(stg_ + row * ROWB + ch * 16);
;         *(u32x4*)(ob + (size_t)row * DM + ch * 8) = v;
;     }
	s_addc_u32 s5, s3, 0
	v_lshlrev_b32_e32 v90, 2, v110
	v_pk_mul_f32 v[22:23], v[84:85], v[84:85]
	v_add_f32_e32 v0, v21, v0
	global_load_dwordx4 v[8:11], v90, s[4:5]
	global_load_dwordx4 v[12:15], v90, s[4:5] offset:32
	v_add_f32_e32 v0, v22, v0
	v_pk_mul_f32 v[88:89], v[24:25], v[24:25]
	v_add_f32_e32 v0, v23, v0
	v_add_f32_e32 v0, v88, v0
	v_pk_mul_f32 v[48:49], v[2:3], v[2:3]
	v_add_f32_e32 v0, v89, v0
	v_add_f32_e32 v0, v48, v0
	v_pk_mul_f32 v[50:51], v[4:5], v[4:5]
	v_add_f32_e32 v0, v49, v0
	v_add_f32_e32 v0, v50, v0
	v_pk_mul_f32 v[52:53], v[6:7], v[6:7]
	global_load_dwordx4 v[26:29], v90, s[4:5] offset:64
	global_load_dwordx4 v[30:33], v90, s[4:5] offset:96
	v_add_f32_e32 v0, v51, v0
	v_add_f32_e32 v0, v52, v0
	v_add_f32_e32 v0, v53, v0
	ds_bpermute_b32 v38, v104, v0
	global_load_dwordx4 v[16:19], v90, s[4:5] offset:128
	global_load_dwordx4 v[34:37], v90, s[4:5] offset:160
	global_load_dwordx4 v[20:23], v90, s[4:5] offset:192
	s_ashr_i32 s3, s2, 31
	s_lshl_b64 s[2:3], s[2:3], 12
	s_waitcnt lgkmcnt(0)
	v_add_f32_e32 v0, v0, v38
	v_fmamk_f32 v0, v0, 0x3c800000, v241
	v_mul_f32_e32 v38, 0x4f800000, v0
	v_cmp_gt_f32_e32 vcc, s85, v0
	v_readlane_b32 s80, v254, 57
	s_mov_b32 s77, 0x8000
	v_cndmask_b32_e32 v0, v0, v38, vcc
	global_load_dwordx4 v[38:41], v90, s[4:5] offset:224
	v_sqrt_f32_e32 v48, v0
	v_readlane_b32 s81, v254, 58
	v_add_u32_e32 v49, -1, v48
	v_fma_f32 v50, -v49, v48, v0
	v_cmp_ge_f32_e64 s[4:5], 0, v50
	v_add_u32_e32 v50, 1, v48
	s_nop 0
	v_cndmask_b32_e64 v49, v48, v49, s[4:5]
	v_fma_f32 v48, -v50, v48, v0
	v_cmp_lt_f32_e64 s[4:5], 0, v48
	s_nop 1
	v_cndmask_b32_e64 v48, v49, v50, s[4:5]
	v_mul_f32_e32 v49, 0x37800000, v48
	v_cndmask_b32_e32 v48, v48, v49, vcc
	v_cmp_class_f32_e32 vcc, v0, v242
	v_mul_u32_u24_e32 v50, 0x90, v102
	v_add3_u32 v50, s1, v50, v103
	v_cndmask_b32_e32 v0, v48, v0, vcc
	v_div_scale_f32 v48, s[4:5], v0, v0, 1.0
	v_rcp_f32_e32 v49, v48
	v_readlane_b32 s4, v251, 41
	v_readlane_b32 s8, v251, 45
	v_readlane_b32 s9, v251, 46
	v_fma_f32 v51, -v48, v49, 1.0
	v_fmac_f32_e32 v49, v51, v49
	v_div_scale_f32 v51, vcc, 1.0, v0, 1.0
	v_mul_f32_e32 v52, v51, v49
	v_fma_f32 v53, -v48, v52, v51
	v_fmac_f32_e32 v52, v53, v49
	v_fma_f32 v48, -v48, v52, v51
	v_div_fmas_f32 v48, v48, v49, v52
	v_div_fixup_f32 v0, v48, v0, 1.0
	v_pk_mul_f32 v[48:49], v[58:59], v[0:1] op_sel_hi:[1,0]
	v_pk_mul_f32 v[2:3], v[2:3], v[0:1] op_sel_hi:[1,0]
	s_add_u32 s2, s8, s2
	s_addc_u32 s3, s9, s3
	s_lshl_b32 s4, s75, 1
	s_add_u32 s2, s2, s4
	s_addc_u32 s3, s3, 0
	v_readlane_b32 s5, v251, 42
	v_readlane_b32 s6, v251, 43
	v_readlane_b32 s7, v251, 44
	v_readlane_b32 s10, v251, 47
	v_readlane_b32 s11, v251, 48
	s_waitcnt vmcnt(0)
	v_pk_mul_f32 v[8:9], v[8:9], v[48:49]
	v_pk_mul_f32 v[48:49], v[54:55], v[0:1] op_sel_hi:[1,0]
	v_cvt_pk_bf16_f32 v8, v8, v9
	v_pk_mul_f32 v[10:11], v[10:11], v[48:49]
	v_pk_mul_f32 v[2:3], v[22:23], v[2:3]
	v_cvt_pk_bf16_f32 v9, v10, v11
	v_pk_mul_f32 v[10:11], v[64:65], v[0:1] op_sel_hi:[1,0]
	s_nop 0
	v_pk_mul_f32 v[10:11], v[12:13], v[10:11]
	v_pk_mul_f32 v[12:13], v[62:63], v[0:1] op_sel_hi:[1,0]
	v_cvt_pk_bf16_f32 v10, v10, v11
	v_pk_mul_f32 v[12:13], v[14:15], v[12:13]
	v_lshrrev_b32_e32 v14, 3, v101
	v_cvt_pk_bf16_f32 v11, v12, v13
	ds_write2_b64 v50, v[8:9], v[10:11] offset1:2
	v_pk_mul_f32 v[8:9], v[70:71], v[0:1] op_sel_hi:[1,0]
	v_pk_mul_f32 v[10:11], v[42:43], v[0:1] op_sel_hi:[1,0]
	v_pk_mul_f32 v[8:9], v[26:27], v[8:9]
	v_pk_mul_f32 v[10:11], v[28:29], v[10:11]
	v_cvt_pk_bf16_f32 v8, v8, v9
	v_cvt_pk_bf16_f32 v9, v10, v11
	v_pk_mul_f32 v[10:11], v[44:45], v[0:1] op_sel_hi:[1,0]
	v_pk_mul_f32 v[12:13], v[46:47], v[0:1] op_sel_hi:[1,0]
	v_pk_mul_f32 v[10:11], v[30:31], v[10:11]
	v_pk_mul_f32 v[12:13], v[32:33], v[12:13]
	v_cvt_pk_bf16_f32 v10, v10, v11
	v_cvt_pk_bf16_f32 v11, v12, v13
	ds_write2_b64 v50, v[8:9], v[10:11] offset0:4 offset1:6
	v_pk_mul_f32 v[8:9], v[80:81], v[0:1] op_sel_hi:[1,0]
	v_pk_mul_f32 v[10:11], v[76:77], v[0:1] op_sel_hi:[1,0]
	v_pk_mul_f32 v[8:9], v[16:17], v[8:9]
	v_pk_mul_f32 v[10:11], v[18:19], v[10:11]
	v_cvt_pk_bf16_f32 v8, v8, v9
	v_cvt_pk_bf16_f32 v9, v10, v11
	v_pk_mul_f32 v[10:11], v[86:87], v[0:1] op_sel_hi:[1,0]
	v_pk_mul_f32 v[12:13], v[84:85], v[0:1] op_sel_hi:[1,0]
	v_pk_mul_f32 v[10:11], v[34:35], v[10:11]
	v_pk_mul_f32 v[12:13], v[36:37], v[12:13]
	v_cvt_pk_bf16_f32 v10, v10, v11
	v_cvt_pk_bf16_f32 v11, v12, v13
	ds_write2_b64 v50, v[8:9], v[10:11] offset0:8 offset1:10
	v_pk_mul_f32 v[8:9], v[24:25], v[0:1] op_sel_hi:[1,0]
	s_nop 0
	v_pk_mul_f32 v[8:9], v[20:21], v[8:9]
	s_nop 0
	v_cvt_pk_bf16_f32 v8, v8, v9
	v_cvt_pk_bf16_f32 v9, v2, v3
	v_pk_mul_f32 v[2:3], v[4:5], v[0:1] op_sel_hi:[1,0]
	v_pk_mul_f32 v[4:5], v[6:7], v[0:1] op_sel_hi:[1,0]
	v_pk_mul_f32 v[2:3], v[38:39], v[2:3]
	v_pk_mul_f32 v[4:5], v[40:41], v[4:5]
	v_cvt_pk_bf16_f32 v2, v2, v3
	v_cvt_pk_bf16_f32 v3, v4, v5
	v_lshlrev_b32_e32 v0, 4, v100
	ds_write2_b64 v50, v[8:9], v[2:3] offset0:12 offset1:14
	v_and_b32_e32 v0, 0x70, v0
	v_mul_u32_u24_e32 v4, 0x90, v14
	s_waitcnt lgkmcnt(0)
	v_add3_u32 v15, s1, v0, v4
	ds_read_b128 v[4:7], v15
	ds_read_b128 v[8:11], v15 offset:1152
	v_lshl_add_u64 v[2:3], s[2:3], 0, v[0:1]
	s_mov_b64 s[2:3], 0x15800c00
	v_lshl_add_u64 v[2:3], v[2:3], 0, s[2:3]
	v_lshlrev_b32_e32 v0, 12, v14
	v_lshl_add_u64 v[12:13], v[2:3], 0, v[0:1]
	s_waitcnt lgkmcnt(1)
	global_store_dwordx4 v[12:13], v[4:7], off sc1
	ds_read_b128 v[4:7], v15 offset:2304
	v_or_b32_e32 v12, 0x8000, v0
	v_mov_b32_e32 v13, v1
	v_lshl_add_u64 v[12:13], v[2:3], 0, v[12:13]
	v_or_b32_e32 v0, 0x10000, v0
	s_waitcnt lgkmcnt(1)
	global_store_dwordx4 v[12:13], v[8:11], off sc1
	s_nop 1
	v_lshl_add_u64 v[8:9], v[2:3], 0, v[0:1]
	s_waitcnt lgkmcnt(0)
	global_store_dwordx4 v[8:9], v[4:7], off sc1
	v_add_u32_e32 v0, 0xd80, v15
	s_nop 0
	v_or_b32_e32 v4, 24, v14
	s_branch .LBB0_522
